# phase-0 silu(c) LDS fill: 10 loads in flight behind counted vmcnt (was 10 serialized round trips), on top of the batched LRU conv-weight staging
# speedup vs baseline: 1.0028x; 1.0028x over previous
; #define LAS __attribute__((address_space(3)))
; __device__ __forceinline__ float sigmoidf_(float x) { return __builtin_amdgcn_rcpf(1.f + __expf(-x)); }
; __device__ __forceinline__ void p0_phase(ArgP a, LAS unsigned char* lds, int tid, int wave, int lane, int bid, int G) {
;     ...
;     LAS float* sl = (LAS float*)lds; LAS float* red = (LAS float*)(lds + 5 * 1024 * 4);
;     for (int i = tid; i < 5 * 1024; i += NTHR) { const int mi = i >> 10, k = i & 1023; const float v = mi < 4 ? a->in[1][mi * 1024 + k] : a->in[3][k]; sl[i] = v * sigmoidf_(v); }
.LBB0_1114:
	s_load_dwordx2 s[12:13], s[30:31], 0x8
	s_load_dwordx2 s[2:3], s[30:31], 0x18
	v_lshlrev_b32_e32 v1, 2, v4
	s_waitcnt lgkmcnt(0)
	global_load_dword v6, v1, s[12:13]
	global_load_dword v7, v1, s[12:13] offset:2048
	s_add_u32 s12, s12, 0x1000
	s_addc_u32 s13, s13, 0
	global_load_dword v8, v1, s[12:13]
	global_load_dword v9, v1, s[12:13] offset:2048
	s_add_u32 s12, s12, 0x1000
	s_addc_u32 s13, s13, 0
	global_load_dword v10, v1, s[12:13]
	global_load_dword v11, v1, s[12:13] offset:2048
	s_add_u32 s12, s12, 0x1000
	s_addc_u32 s13, s13, 0
	global_load_dword v12, v1, s[12:13]
	global_load_dword v13, v1, s[12:13] offset:2048
	global_load_dword v14, v1, s[2:3]
	global_load_dword v15, v1, s[2:3] offset:2048
	s_waitcnt vmcnt(9)
	v_mul_f32_e32 v3, 0xbfb8aa3b, v6
	v_exp_f32_e32 v3, v3
	s_nop 0
	v_add_f32_e32 v3, 1.0, v3
	v_rcp_f32_e32 v3, v3
	s_nop 0
	v_mul_f32_e32 v3, v6, v3
	ds_write_b32 v1, v3
	s_waitcnt vmcnt(8)
	v_mul_f32_e32 v3, 0xbfb8aa3b, v7
	v_exp_f32_e32 v3, v3
	s_nop 0
	v_add_f32_e32 v3, 1.0, v3
	v_rcp_f32_e32 v3, v3
	s_nop 0
	v_mul_f32_e32 v3, v7, v3
	ds_write_b32 v1, v3 offset:2048
	s_waitcnt vmcnt(7)
	v_mul_f32_e32 v3, 0xbfb8aa3b, v8
	v_exp_f32_e32 v3, v3
	s_nop 0
	v_add_f32_e32 v3, 1.0, v3
	v_rcp_f32_e32 v3, v3
	s_nop 0
	v_mul_f32_e32 v3, v8, v3
	ds_write_b32 v1, v3 offset:4096
	s_waitcnt vmcnt(6)
	v_mul_f32_e32 v3, 0xbfb8aa3b, v9
	v_exp_f32_e32 v3, v3
	s_nop 0
	v_add_f32_e32 v3, 1.0, v3
	v_rcp_f32_e32 v3, v3
	s_nop 0
	v_mul_f32_e32 v3, v9, v3
	ds_write_b32 v1, v3 offset:6144
	s_waitcnt vmcnt(5)
	v_mul_f32_e32 v3, 0xbfb8aa3b, v10
	v_exp_f32_e32 v3, v3
	s_nop 0
	v_add_f32_e32 v3, 1.0, v3
	v_rcp_f32_e32 v3, v3
	s_nop 0
	v_mul_f32_e32 v3, v10, v3
	ds_write_b32 v1, v3 offset:8192
	s_waitcnt vmcnt(4)
	v_mul_f32_e32 v3, 0xbfb8aa3b, v11
	v_exp_f32_e32 v3, v3
	s_nop 0
	v_add_f32_e32 v3, 1.0, v3
	v_rcp_f32_e32 v3, v3
	s_nop 0
	v_mul_f32_e32 v3, v11, v3
	ds_write_b32 v1, v3 offset:10240
	s_waitcnt vmcnt(3)
	v_mul_f32_e32 v3, 0xbfb8aa3b, v12
	v_exp_f32_e32 v3, v3
	s_nop 0
	v_add_f32_e32 v3, 1.0, v3
	v_rcp_f32_e32 v3, v3
	s_nop 0
	v_mul_f32_e32 v3, v12, v3
	ds_write_b32 v1, v3 offset:12288
	s_waitcnt vmcnt(2)
	v_mul_f32_e32 v3, 0xbfb8aa3b, v13
	v_exp_f32_e32 v3, v3
	s_nop 0
	v_add_f32_e32 v3, 1.0, v3
	v_rcp_f32_e32 v3, v3
	s_nop 0
	v_mul_f32_e32 v3, v13, v3
	ds_write_b32 v1, v3 offset:14336
	s_waitcnt vmcnt(1)
	v_mul_f32_e32 v3, 0xbfb8aa3b, v14
	v_exp_f32_e32 v3, v3
	s_nop 0
	v_add_f32_e32 v3, 1.0, v3
	v_rcp_f32_e32 v3, v3
	s_nop 0
	v_mul_f32_e32 v3, v14, v3
	ds_write_b32 v1, v3 offset:16384
	s_waitcnt vmcnt(0)
	v_mul_f32_e32 v3, 0xbfb8aa3b, v15
	v_exp_f32_e32 v3, v3
	s_nop 0
	v_add_f32_e32 v3, 1.0, v3
	v_rcp_f32_e32 v3, v3
	s_nop 0
	v_mul_f32_e32 v3, v15, v3
	ds_write_b32 v1, v3 offset:18432
